# attention tile loop: three address VALU moved behind the 4th QK MFMA to fill its mandatory wait states (s_nop 6 -> s_nop 3), cost-weighted VALU spacing; on top of v40
# speedup vs baseline: 1.0028x; 1.0028x over previous
.LBB0_545:
	s_add_i32 s72, s87, s59
	v_mov_b32_e32 v195, v131
	s_cmp_lt_i32 s72, s58
	s_mov_b32 s72, s93
	s_cbranch_scc1 .LBB0_544
	s_add_i32 s80, s87, s77
	s_lshr_b32 s80, s80, 2
	v_bitop3_b32 v6, s80, v142, v1 bitop3:0x36
	v_lshlrev_b32_e32 v28, 3, v6
	v_or_b32_e32 v27, s80, v1
	s_waitcnt lgkmcnt(0)
	v_mfma_f32_32x32x16_bf16 v[2:17], v[240:243], v[114:117], 0
	v_bitop3_b32 v22, v27, v142, 2 bitop3:0x36
	v_lshlrev_b32_e32 v30, 3, v22
	v_bitop3_b32 v22, v27, v142, 4 bitop3:0x36
	v_lshlrev_b32_e32 v32, 3, v22
	s_waitcnt lgkmcnt(1)
	v_mfma_f32_32x32x16_bf16 v[2:17], v[244:247], v[118:121], v[2:17]
	v_bitop3_b32 v18, v27, v142, 6 bitop3:0x36
	v_lshlrev_b32_e32 v27, 3, v18
	v_add_u32_e32 v29, v202, v28
	v_add_u32_e32 v132, v202, v27
	s_waitcnt lgkmcnt(1)
	v_mfma_f32_32x32x16_bf16 v[2:17], v[248:251], v[122:125], v[2:17]
	v_add_u32_e32 v22, v203, v28
	v_add_u32_e32 v31, v202, v30
	v_add_u32_e32 v33, v202, v32
	ds_read_b64 v[138:139], v29 offset:49152
	ds_read_b64 v[140:141], v31 offset:49152
	ds_read_b64 v[130:131], v33 offset:49152
	ds_read_b64 v[132:133], v132 offset:49152
	s_waitcnt lgkmcnt(4)
	v_mfma_f32_32x32x16_bf16 v[2:17], v[252:255], v[126:129], v[2:17]
	v_add_u32_e32 v23, v203, v30
	v_add_u32_e32 v24, v203, v32
	v_add_u32_e32 v25, v203, v27
	ds_read_b64 v[218:219], v22 offset:24576
	ds_read_b64 v[220:221], v23 offset:24576
	ds_read_b64 v[134:135], v24 offset:24576
	ds_read_b64 v[136:137], v25 offset:24576
	s_add_i32 s90, s90, -1
	s_nop 3
	v_min_f32_e64 v3, -v3, s98
	v_exp_f32_e32 v3, v3
	v_min_f32_e64 v5, -v5, s98
	v_min_f32_e64 v4, -v4, s98
	v_add_f32_e32 v19, 1.0, v3
	v_exp_f32_e32 v194, v5
	v_min_f32_e64 v5, -v6, s98
	v_rcp_f32_e32 v169, v19
	v_exp_f32_e32 v4, v4
	v_exp_f32_e32 v6, v5
	v_min_f32_e64 v5, -v7, s98
	v_exp_f32_e32 v7, v5
	v_mul_f32_e32 v20, v3, v169
	v_add_f32_e32 v3, 1.0, v4
	v_rcp_f32_e32 v22, v3
	v_add_f32_e32 v3, 1.0, v194
	v_rcp_f32_e32 v24, v3
	v_add_f32_e32 v3, 1.0, v6
	v_rcp_f32_e32 v26, v3
	v_add_f32_e32 v3, 1.0, v7
	v_rcp_f32_e32 v27, v3
	v_min_f32_e64 v3, -v8, s98
	v_exp_f32_e32 v8, v3
	v_min_f32_e64 v3, -v9, s98
	v_exp_f32_e32 v9, v3
	v_add_f32_e32 v3, 1.0, v8
	v_rcp_f32_e32 v28, v3
	v_min_f32_e64 v5, -v12, s98
	v_add_f32_e32 v3, 1.0, v9
	v_rcp_f32_e32 v29, v3
	v_min_f32_e64 v3, -v10, s98
	v_exp_f32_e32 v10, v3
	v_min_f32_e64 v3, -v11, s98
	v_exp_f32_e32 v11, v5
	v_min_f32_e64 v5, -v13, s98
	v_exp_f32_e32 v31, v5
	v_min_f32_e64 v5, -v14, s98
	v_exp_f32_e32 v30, v3
	v_exp_f32_e32 v12, v5
	v_min_f32_e64 v5, -v15, s98
	v_exp_f32_e32 v14, v5
	v_min_f32_e64 v5, -v16, s98
	v_add_f32_e32 v3, 1.0, v10
	v_rcp_f32_e32 v226, v3
	v_add_f32_e32 v3, 1.0, v30
	v_exp_f32_e32 v13, v5
	v_min_f32_e64 v5, -v17, s98
	v_rcp_f32_e32 v228, v3
	v_add_f32_e32 v3, 1.0, v11
	v_rcp_f32_e32 v227, v3
	v_add_f32_e32 v3, 1.0, v31
	v_exp_f32_e32 v15, v5
	v_rcp_f32_e32 v229, v3
	v_add_f32_e32 v3, 1.0, v12
	v_rcp_f32_e32 v230, v3
	v_add_f32_e32 v3, 1.0, v14
	v_rcp_f32_e32 v16, v3
	v_add_f32_e32 v3, 1.0, v13
	v_rcp_f32_e32 v231, v3
	v_add_f32_e32 v3, 1.0, v15
	v_rcp_f32_e32 v17, v3
	v_min_f32_e64 v2, -v2, s98
	v_exp_f32_e32 v2, v2
	v_pk_mul_f32 v[12:13], v[12:13], v[230:231]
	v_pk_mul_f32 v[14:15], v[14:15], v[16:17]
	v_pk_mul_f32 v[6:7], v[6:7], v[26:27]
	v_pk_mul_f32 v[224:225], v[12:13], v[14:15]
	v_add_f32_e32 v18, 1.0, v2
	v_mul_f32_e32 v3, v224, v225
	v_mov_b32_e32 v238, v3
	v_mov_b32_e32 v5, v3
	s_nop 1
	v_permlane32_swap_b32_e32 v238, v5
	s_nop 0
	v_cndmask_b32_e64 v5, v238, v5, s[0:1]
	v_rcp_f32_e32 v18, v18
	v_pk_mul_f32 v[8:9], v[8:9], v[28:29]
	v_pk_mul_f32 v[10:11], v[10:11], v[226:227]
	v_pk_mul_f32 v[232:233], v[30:31], v[228:229]
	v_pk_mul_f32 v[32:33], v[6:7], v[6:7] op_sel_hi:[0,1]
	v_pk_mul_f32 v[222:223], v[8:9], v[8:9] op_sel_hi:[0,1]
	v_pk_mul_f32 v[30:31], v[10:11], v[232:233]
	s_waitcnt lgkmcnt(0)
	v_mul_f32_e32 v25, v3, v5
	v_pk_mul_f32 v[30:31], v[30:31], v[30:31] op_sel:[0,1] op_sel_hi:[1,0]
	v_mov_b32_e32 v3, v33
	v_mov_b32_e32 v19, v223
	v_mov_b32_e32 v238, v30
	v_mov_b32_e32 v23, v30
	s_nop 1
	v_permlane32_swap_b32_e32 v238, v23
	s_nop 0
	v_cndmask_b32_e64 v23, v238, v23, s[0:1]
	v_pk_mul_f32 v[2:3], v[2:3], v[18:19]
	v_mul_f32_e32 v6, v195, v5
	v_mov_b32_e32 v238, v3
	v_mov_b32_e32 v21, v3
	s_nop 1
	v_permlane32_swap_b32_e32 v238, v21
	s_nop 0
	v_cndmask_b32_e64 v21, v238, v21, s[0:1]
	v_cndmask_b32_e64 v225, v195, v6, s[0:1]
	v_mul_f32_e32 v224, v15, v225
	v_mul_f32_e32 v13, v13, v224
	v_mov_b32_e32 v5, v30
	v_mul_f32_e32 v12, v14, v13
	v_pk_mul_f32 v[14:15], v[194:195], v[24:25]
	s_waitcnt lgkmcnt(1)
	v_pk_mul_f32 v[4:5], v[4:5], v[22:23]
	v_mov_b32_e32 v234, v231
	v_mov_b32_e32 v235, v17
	v_mov_b32_e32 v231, v16
	v_pk_mul_f32 v[16:17], v[4:5], v[14:15]
	s_waitcnt lgkmcnt(0)
	v_pk_mul_f32 v[2:3], v[2:3], v[20:21]
	v_mul_f32_e32 v10, v15, v23
	v_pk_mul_f32 v[236:237], v[2:3], v[16:17]
	v_mov_b32_e32 v238, v236
	v_mov_b32_e32 v171, v236
	s_nop 1
	v_permlane32_swap_b32_e32 v238, v171
	s_nop 0
	v_cndmask_b32_e64 v171, v238, v171, s[0:1]
	v_mul_f32_e32 v2, v17, v21
	v_cndmask_b32_e64 v3, v17, v2, s[0:1]
	v_mul_f32_e32 v2, v9, v3
	v_pk_mul_f32 v[16:17], v[28:29], v[2:3]
	v_mul_f32_e32 v3, v8, v2
	s_waitcnt lgkmcnt(0)
	v_mul_f32_e32 v5, v237, v171
	v_mul_f32_e32 v2, v7, v3
	v_cndmask_b32_e64 v7, v237, v5, s[0:1]
	v_mul_f32_e32 v6, v14, v7
	v_mul_f32_e32 v5, v4, v6
	v_pk_mul_f32 v[2:3], v[26:27], v[2:3]
	v_mov_b32_e32 v23, v24
	v_mul_f32_e32 v4, v20, v5
	v_mov_b32_e32 v19, v169
	v_pk_mul_f32 v[234:235], v[234:235], v[224:225]
	v_pk_mul_f32 v[8:9], v[22:23], v[6:7]
	v_pk_mul_f32 v[4:5], v[18:19], v[4:5]
	v_cvt_pk_bf16_f32 v224, v2, v3
	v_cndmask_b32_e64 v3, v15, v10, s[0:1]
	v_cvt_pk_bf16_f32 v222, v4, v5
	v_cvt_pk_bf16_f32 v223, v8, v9
	v_cvt_pk_bf16_f32 v225, v16, v17
	v_mul_f32_e32 v2, v233, v3
	v_mov_b32_e32 v4, v227
	v_mov_b32_e32 v5, v229
	v_mfma_f32_32x32x16_bf16 v[50:65], v[138:141], v[222:225], v[50:65]
	v_mul_f32_e64 v140, v230, v12
	v_mul_f32_e64 v141, v231, v13
	v_mul_f32_e64 v230, v4, v2
	v_mul_f32_e64 v231, v5, v3
	v_mul_f32_e32 v139, v11, v2
	v_mul_f32_e32 v138, v232, v139
	v_mov_b32_e32 v227, v228
	v_pk_mul_f32 v[138:139], v[226:227], v[138:139]
	v_cvt_pk_bf16_f32 v140, v140, v141
	v_mfma_f32_32x32x16_bf16 v[34:49], v[218:221], v[222:225], v[34:49]
	v_cvt_pk_bf16_f32 v138, v138, v139
	v_cvt_pk_bf16_f32 v139, v230, v231
	v_cvt_pk_bf16_f32 v141, v234, v235
	s_nop 1
	v_mfma_f32_32x32x16_bf16 v[50:65], v[130:133], v[138:141], v[50:65]
	v_mul_f32_e32 v130, v236, v171
	v_mul_f32_e32 v131, v130, v237
	v_cmp_gt_f32_e32 vcc, s88, v131
	s_cmp_lg_u64 vcc, exec
	v_mfma_f32_32x32x16_bf16 v[34:49], v[134:137], v[138:141], v[34:49]
	s_cbranch_scc0 .LBB0_548
; #define LAS __attribute__((address_space(3)))
; __device__ __forceinline__ void attn_load_k(bf16x8 (&kf)[4], bool in_lds, LAS unsigned char* KL, int kl0, const bf16_t* kg, int ql, int hi) {
;     if (in_lds) { const int r = kl0 + ql; LAS unsigned char* rp = KL + r * 128; const int sw = (r >> 1) & 7;
; #pragma unroll
;         for (int kk = 0; kk < 4; ++kk) kf[kk] = *(const LAS bf16x8*)(rp + (((2 * kk + hi) ^ sw) << 4));
; __device__ __forceinline__ void attn_phase(LAS unsigned char* lds, const bf16_t* Q, const bf16_t* Kb, const bf16_t* VT, const bf16_t* Zs, bf16_t* OZ, int vcu, int G) {
;     ...
;             ATT_TILE(false)
;             if (__all(carry < STOP)) break;
	s_add_i32 s93, s72, -1
	s_sub_i32 s77, s77, 32
	s_sub_i32 s59, s59, 32
	s_cmp_lt_i32 s93, 2
	s_mov_b32 s94, -1
	v_subrev_u32_e32 v165, 32, v165
	v_add_u32_e32 v167, 0xfffff000, v167
	s_cselect_b64 s[80:81], -1, 0
	s_mov_b64 s[82:83], 0
	s_and_b64 vcc, exec, s[80:81]
	v_add_u32_e32 v255, s87, v165
	v_lshrrev_b32_e32 v255, 1, v255
	v_bitop3_b32 v240, v255, v1, 7 bitop3:0x6c
	v_lshl_add_u32 v240, v240, 4, v167
	ds_read_b128 v[240:243], v240
	v_bitop3_b32 v244, v255, v143, 7 bitop3:0x6c
	v_lshl_add_u32 v244, v244, 4, v167
	ds_read_b128 v[244:247], v244
	v_bitop3_b32 v248, v255, v147, 7 bitop3:0x6c
	v_lshl_add_u32 v248, v248, 4, v167
	ds_read_b128 v[248:251], v248
	v_bitop3_b32 v252, v255, v149, 7 bitop3:0x6c
	v_lshl_add_u32 v252, v252, 4, v167
	ds_read_b128 v[252:255], v252
	s_cbranch_vccz .LBB0_545
	s_branch .LBB0_549
